# loop-edge: 64-byte alignment of the two top-k loop heads and the pool-fold loop head (on top of K-loop alignment)
# speedup vs baseline: 1.0189x; 1.0080x over previous
; #define LDS_FENCE() asm volatile("s_waitcnt lgkmcnt(0)" ::: "memory")
; DI void nsa_wg_unit(const Args& a, int l, int b, int g, int tb, unsigned char* lds, int tid_in, bool stage) {
;     ...
;       for (int c = 0; c < CPL; ++c) { const int j = qtr * CPL + c; float v = IA[tok * 65 + j] + IB[tok * 65 + j]; const bool forced = (j == 0) | (j == jt) | (j == jt - 1); v = forced ? 1e6f : (j > jt ? -1e30f : v); mv[c] = v; }
;       LDS_FENCE();
; #pragma unroll
;       for (int c = 0; c < CPL; ++c) IA[tok * 65 + qtr * CPL + c] = mv[c];
;       LDS_FENCE();
;       int cnt[CPL];
; #pragma unroll
;       for (int c = 0; c < CPL; ++c) cnt[c] = (qtr * CPL + c <= jt) ? 0 : 64;
;       if (jt >= 16)
; #pragma unroll 4
;       for (int i = 0; i < 64; ++i) { const float vi = IA[tok * 65 + i];
; #pragma unroll
;           for (int c = 0; c < CPL; ++c) { const int j = qtr * CPL + c; cnt[c] += ((vi > mv[c]) || (vi == mv[c] && i < j)) ? 1 : 0; } }
.LBB0_154:
	s_or_b64 exec, exec, s[0:1]
	v_cmp_lt_u32_e32 vcc, s33, v0
	v_mul_u32_u24_e32 v30, 0x104, v1
	v_lshlrev_b32_e32 v1, 5, v32
	v_cndmask_b32_e64 v34, 0, 64, vcc
	v_cmp_gt_u32_e32 vcc, s33, v0
	v_add3_u32 v1, s9, v30, v1
	s_waitcnt lgkmcnt(0)
	ds_write2_b32 v1, v4, v2 offset1:1
	ds_write2_b32 v1, v10, v8 offset0:2 offset1:3
	ds_write2_b32 v1, v18, v16 offset0:4 offset1:5
	ds_write2_b32 v1, v26, v24 offset0:6 offset1:7
	v_cndmask_b32_e64 v37, 64, 0, vcc
	v_cmp_lt_u32_e32 vcc, s33, v6
	s_waitcnt lgkmcnt(0)
	s_cmp_lt_u32 s33, 16
	s_nop 0
	v_cndmask_b32_e64 v40, 0, 64, vcc
	v_cmp_lt_u32_e32 vcc, s33, v12
	s_nop 1
	v_cndmask_b32_e64 v45, 0, 64, vcc
	v_cmp_lt_u32_e32 vcc, s33, v14
	s_nop 1
	v_cndmask_b32_e64 v46, 0, 64, vcc
	v_cmp_lt_u32_e32 vcc, s33, v20
	s_nop 1
	v_cndmask_b32_e64 v42, 0, 64, vcc
	v_cmp_lt_u32_e32 vcc, s33, v22
	s_nop 1
	v_cndmask_b32_e64 v38, 0, 64, vcc
	v_cmp_lt_u32_e32 vcc, s33, v28
	s_nop 1
	v_cndmask_b32_e64 v35, 0, 64, vcc
	s_cbranch_scc1 .LBB0_158
	v_mov_b32_e32 v1, v4
	v_mov_b32_e32 v3, v0
	v_mov_b32_e32 v5, v2
	v_mov_b32_e32 v7, v10
	v_mov_b32_e32 v9, v6
	v_mov_b32_e32 v11, v8
	v_mov_b32_e32 v13, v12
	v_mov_b32_e32 v15, v18
	v_mov_b32_e32 v17, v14
	v_mov_b32_e32 v19, v16
	v_mov_b32_e32 v21, v20
	v_mov_b32_e32 v23, v26
	v_mov_b32_e32 v25, v22
	v_mov_b32_e32 v27, v24
	v_mov_b32_e32 v29, v28
	v_add_u32_e32 v33, s8, v30
	s_mov_b32 s0, 1
	s_mov_b32 s1, 0
	v_mov_b32_e32 v36, 0
	v_mov_b32_e32 v39, 0
	v_mov_b32_e32 v43, 0
	v_mov_b32_e32 v47, 0
	v_mov_b32_e32 v49, 0
	v_mov_b32_e32 v48, 0
	v_mov_b32_e32 v44, 0
	v_mov_b32_e32 v41, 0
	s_mov_b32 s19, 0
	v_add_u32_e32 v33, 0x19e00, v33
	v_mov_b32_e32 v68, 0x80000001
	v_ashrrev_i32_e32 v31, 31, v4
	v_or_b32_e32 v31, 1, v31
	v_sub_u32_e32 v1, v4, v31
	v_cmp_eq_u32_e32 vcc, 0, v4
	s_nop 1
	v_cndmask_b32_e32 v1, v1, v68, vcc
	v_ashrrev_i32_e32 v31, 31, v2
	v_or_b32_e32 v31, 1, v31
	v_sub_u32_e32 v3, v2, v31
	v_cmp_eq_u32_e32 vcc, 0, v2
	s_nop 1
	v_cndmask_b32_e32 v3, v3, v68, vcc
	v_ashrrev_i32_e32 v31, 31, v10
	v_or_b32_e32 v31, 1, v31
	v_sub_u32_e32 v5, v10, v31
	v_cmp_eq_u32_e32 vcc, 0, v10
	s_nop 1
	v_cndmask_b32_e32 v5, v5, v68, vcc
	v_ashrrev_i32_e32 v31, 31, v8
	v_or_b32_e32 v31, 1, v31
	v_sub_u32_e32 v7, v8, v31
	v_cmp_eq_u32_e32 vcc, 0, v8
	s_nop 1
	v_cndmask_b32_e32 v7, v7, v68, vcc
	v_ashrrev_i32_e32 v31, 31, v18
	v_or_b32_e32 v31, 1, v31
	v_sub_u32_e32 v9, v18, v31
	v_cmp_eq_u32_e32 vcc, 0, v18
	s_nop 1
	v_cndmask_b32_e32 v9, v9, v68, vcc
	v_ashrrev_i32_e32 v31, 31, v16
	v_or_b32_e32 v31, 1, v31
	v_sub_u32_e32 v11, v16, v31
	v_cmp_eq_u32_e32 vcc, 0, v16
	s_nop 1
	v_cndmask_b32_e32 v11, v11, v68, vcc
	v_ashrrev_i32_e32 v31, 31, v26
	v_or_b32_e32 v31, 1, v31
	v_sub_u32_e32 v13, v26, v31
	v_cmp_eq_u32_e32 vcc, 0, v26
	s_nop 1
	v_cndmask_b32_e32 v13, v13, v68, vcc
	v_ashrrev_i32_e32 v31, 31, v24
	v_or_b32_e32 v31, 1, v31
	v_sub_u32_e32 v15, v24, v31
	v_cmp_eq_u32_e32 vcc, 0, v24
	s_nop 1
	v_cndmask_b32_e32 v15, v15, v68, vcc
	s_add_i32 s98, s33, 8
	s_lshr_b32 s98, s98, 3
	s_mov_b32 s99, 0
	.p2align	6

; #define LDS_FENCE() asm volatile("s_waitcnt lgkmcnt(0)" ::: "memory")
; DI void nsa_wg_unit(const Args& a, int l, int b, int g, int tb, unsigned char* lds, int tid_in, bool stage) {
;     ...
;       for (int c = 0; c < CPL; ++c) { const int j = qtr * CPL + c; float v = IA[tok * 65 + j] + IB[tok * 65 + j]; const bool forced = (j == 0) | (j == jt) | (j == jt - 1); v = forced ? 1e6f : (j > jt ? -1e30f : v); mv[c] = v; }
;       LDS_FENCE();
; #pragma unroll
;       for (int c = 0; c < CPL; ++c) IA[tok * 65 + qtr * CPL + c] = mv[c];
;       LDS_FENCE();
;       int cnt[CPL];
; #pragma unroll
;       for (int c = 0; c < CPL; ++c) cnt[c] = (qtr * CPL + c <= jt) ? 0 : 64;
;       if (jt >= 16)
; #pragma unroll 4
;       for (int i = 0; i < 64; ++i) { const float vi = IA[tok * 65 + i];
; #pragma unroll
;           for (int c = 0; c < CPL; ++c) { const int j = qtr * CPL + c; cnt[c] += ((vi > mv[c]) || (vi == mv[c] && i < j)) ? 1 : 0; } }
.LBB0_233:
	s_or_b64 exec, exec, s[0:1]
	v_cmp_lt_u32_e32 vcc, s93, v28
	v_mul_u32_u24_e32 v1, 0x104, v30
	v_lshlrev_b32_e32 v3, 5, v32
	v_cndmask_b32_e64 v34, 0, 64, vcc
	v_cmp_lt_u32_e32 vcc, s93, v22
	v_add3_u32 v1, s9, v1, v3
	s_waitcnt lgkmcnt(0)
	ds_write2_b32 v1, v4, v2 offset1:1
	ds_write2_b32 v1, v10, v8 offset0:2 offset1:3
	ds_write2_b32 v1, v18, v16 offset0:4 offset1:5
	ds_write2_b32 v1, v26, v24 offset0:6 offset1:7
	v_cndmask_b32_e64 v37, 0, 64, vcc
	v_cmp_lt_u32_e32 vcc, s93, v20
	s_waitcnt lgkmcnt(0)
	v_mov_b32_e32 v31, s8
	s_movk_i32 s1, 0x104
	v_cndmask_b32_e64 v41, 0, 64, vcc
	v_cmp_lt_u32_e32 vcc, s93, v14
	s_mov_b32 s0, 0
	v_mov_b32_e32 v1, v24
	v_cndmask_b32_e64 v45, 0, 64, vcc
	v_cmp_lt_u32_e32 vcc, s93, v12
	v_mov_b32_e32 v3, v4
	v_mov_b32_e32 v5, v0
	v_cndmask_b32_e64 v48, 0, 64, vcc
	v_cmp_lt_u32_e32 vcc, s93, v6
	v_mov_b32_e32 v7, v2
	v_mov_b32_e32 v9, v10
	v_cndmask_b32_e64 v44, 0, 64, vcc
	v_cmp_gt_u32_e32 vcc, s93, v0
	v_mov_b32_e32 v11, v6
	v_mov_b32_e32 v13, v8
	v_cndmask_b32_e64 v40, 64, 0, vcc
	v_cmp_lt_u32_e32 vcc, s93, v0
	v_mov_b32_e32 v15, v12
	v_mov_b32_e32 v17, v18
	v_cndmask_b32_e64 v36, 0, 64, vcc
	v_mov_b32_e32 v19, v14
	v_mov_b32_e32 v21, v16
	v_mov_b32_e32 v23, v20
	v_mov_b32_e32 v25, v26
	v_mov_b32_e32 v27, v22
	v_mov_b32_e32 v29, v28
	v_mad_u32_u24 v33, v30, s1, v31
	s_mov_b32 s1, 1
	v_mov_b32_e32 v35, 0
	v_mov_b32_e32 v38, 0
	v_mov_b32_e32 v42, 0
	v_mov_b32_e32 v46, 0
	v_mov_b32_e32 v49, 0
	v_mov_b32_e32 v47, 0
	v_mov_b32_e32 v43, 0
	v_mov_b32_e32 v39, 0
	s_mov_b32 s17, 0
	v_add_u32_e32 v33, 0x19e00, v33
	v_mov_b32_e32 v68, 0x80000001
	v_ashrrev_i32_e32 v31, 31, v4
	v_or_b32_e32 v31, 1, v31
	v_sub_u32_e32 v1, v4, v31
	v_cmp_eq_u32_e32 vcc, 0, v4
	s_nop 1
	v_cndmask_b32_e32 v1, v1, v68, vcc
	v_ashrrev_i32_e32 v31, 31, v2
	v_or_b32_e32 v31, 1, v31
	v_sub_u32_e32 v3, v2, v31
	v_cmp_eq_u32_e32 vcc, 0, v2
	s_nop 1
	v_cndmask_b32_e32 v3, v3, v68, vcc
	v_ashrrev_i32_e32 v31, 31, v10
	v_or_b32_e32 v31, 1, v31
	v_sub_u32_e32 v5, v10, v31
	v_cmp_eq_u32_e32 vcc, 0, v10
	s_nop 1
	v_cndmask_b32_e32 v5, v5, v68, vcc
	v_ashrrev_i32_e32 v31, 31, v8
	v_or_b32_e32 v31, 1, v31
	v_sub_u32_e32 v7, v8, v31
	v_cmp_eq_u32_e32 vcc, 0, v8
	s_nop 1
	v_cndmask_b32_e32 v7, v7, v68, vcc
	v_ashrrev_i32_e32 v31, 31, v18
	v_or_b32_e32 v31, 1, v31
	v_sub_u32_e32 v9, v18, v31
	v_cmp_eq_u32_e32 vcc, 0, v18
	s_nop 1
	v_cndmask_b32_e32 v9, v9, v68, vcc
	v_ashrrev_i32_e32 v31, 31, v16
	v_or_b32_e32 v31, 1, v31
	v_sub_u32_e32 v11, v16, v31
	v_cmp_eq_u32_e32 vcc, 0, v16
	s_nop 1
	v_cndmask_b32_e32 v11, v11, v68, vcc
	v_ashrrev_i32_e32 v31, 31, v26
	v_or_b32_e32 v31, 1, v31
	v_sub_u32_e32 v13, v26, v31
	v_cmp_eq_u32_e32 vcc, 0, v26
	s_nop 1
	v_cndmask_b32_e32 v13, v13, v68, vcc
	v_ashrrev_i32_e32 v31, 31, v24
	v_or_b32_e32 v31, 1, v31
	v_sub_u32_e32 v15, v24, v31
	v_cmp_eq_u32_e32 vcc, 0, v24
	s_nop 1
	v_cndmask_b32_e32 v15, v15, v68, vcc
	s_add_i32 s98, s93, 8
	s_lshr_b32 s98, s98, 3
	s_mov_b32 s99, 0
	.p2align	6

; DI void pool_fold_item(const float* __restrict__ win, const float* __restrict__ pw, const float* __restrict__ psc, const float* __restrict__ g1, bf16_t* WIN, int item, int lane) {
;     const int kt = item >> 4, nt = item & 15, np = nt * 32 + (lane & 31), gi = np >> 7, d = np & 127, kb = kt * 8 + (lane >> 5) * 4;
;     const float* wp = pw + (size_t)gi * 128 * 128 + d; const float sc = psc[np];
;     const float* wr = win + (size_t)kb * NIN + C_PL + gi * 128;
;     float acc[4] = {0.f, 0.f, 0.f, 0.f};
; #pragma unroll 16
;     for (int c = 0; c < 128; ++c) { const float w = wp[(size_t)c * 128];
.LBB0_756:
	s_andn2_b64 vcc, exec, s[0:1]
	s_cbranch_vccnz .LBB0_760
	s_lshl_b32 s0, s20, 2
	s_and_b32 s0, s0, 0x30000
	s_and_b32 s6, s22, 0x60
	s_add_u32 s0, s18, s0
	s_addc_u32 s1, s19, 0
	s_add_i32 s7, s24, 0xffffef00
	s_lshl_b32 s12, s7, 5
	s_and_b32 s12, s12, 0x1e0
	v_or_b32_e32 v9, s12, v3
	v_readlane_b32 s44, v253, 51
	v_lshlrev_b32_e32 v8, 2, v9
	v_readlane_b32 s46, v253, 53
	v_readlane_b32 s47, v253, 54
	v_readlane_b32 s45, v253, 52
	v_readlane_b32 s48, v253, 55
	v_readlane_b32 s49, v253, 56
	v_readlane_b32 s50, v253, 57
	v_readlane_b32 s51, v253, 58
	global_load_dword v8, v8, s[46:47]
	v_readlane_b32 s52, v253, 59
	v_readlane_b32 s53, v253, 60
	v_readlane_b32 s54, v253, 61
	v_readlane_b32 s55, v253, 62
	v_readlane_b32 s56, v253, 63
	v_readlane_b32 s57, v254, 0
	v_readlane_b32 s58, v254, 1
	v_readlane_b32 s59, v254, 2
	v_or_b32_e32 v10, s6, v3
	v_lshlrev_b32_sdwa v160, v224, v10 dst_sel:DWORD dst_unused:UNUSED_PAD src0_sel:DWORD src1_sel:WORD_0
	v_readlane_b32 s44, v253, 35
	v_lshl_add_u64 v[10:11], s[0:1], 0, v[160:161]
	s_lshl_b32 s0, s22, 2
	s_lshr_b32 s1, s7, 1
	v_readlane_b32 s45, v253, 36
	v_readlane_b32 s48, v253, 39
	v_readlane_b32 s49, v253, 40
	s_and_b32 s0, s0, 0x600
	s_and_b32 s1, s1, 0x3f8
	s_mov_b64 s[44:45], s[48:49]
	s_add_u32 s0, s44, s0
	v_or_b32_e32 v21, s1, v36
	s_addc_u32 s1, s45, 0
	v_mov_b64_e32 v[12:13], s[0:1]
	v_mad_u64_u32 v[12:13], s[0:1], v21, s41, v[12:13]
	v_mov_b32_e32 v14, 0
	s_mov_b64 s[0:1], 0
	v_mov_b32_e32 v15, v14
	v_mov_b32_e32 v16, v14
	v_mov_b32_e32 v17, v14
	v_readlane_b32 s46, v253, 37
	v_readlane_b32 s47, v253, 38
	v_readlane_b32 s50, v253, 41
	v_readlane_b32 s51, v253, 42
	v_readlane_b32 s52, v253, 43
	v_readlane_b32 s53, v253, 44
	v_readlane_b32 s54, v253, 45
	v_readlane_b32 s55, v253, 46
	v_readlane_b32 s56, v253, 47
	v_readlane_b32 s57, v253, 48
	v_readlane_b32 s58, v253, 49
	v_readlane_b32 s59, v253, 50
	.p2align	6
